# combo18 with a four-group PD schedule (bid bits 5,6 select one of four interleavings of the 4 mLSTM and 2 SSD items)
# baseline (speedup 1.0000x reference)
.LBB0_137:
	v_readlane_b32 s0, v251, 47
	v_readlane_b32 s1, v251, 48
	s_andn2_b64 vcc, exec, s[0:1]
	v_readlane_b32 s14, v253, 60
	s_mov_b32 s15, s57
	s_mov_b32 s16, s57
	s_cbranch_vccnz .Lpd_not
	s_mov_b32 s32, 0
	s_cmpk_lg_u32 s36, 0x100
	s_cbranch_scc1 .LBB0_199
	s_bfe_u32 s2, s57, 0x20005
	s_mov_b32 s32, 0xf543210
	s_cmp_eq_u32 s2, 1
	s_cselect_b32 s32, 0xf321054, s32
	s_cmp_eq_u32 s2, 2
	s_cselect_b32 s32, 0xf325410, s32
	s_cmp_eq_u32 s2, 3
	s_cselect_b32 s32, 0xf532104, s32
	s_and_b32 s2, s32, 15
	s_lshl_b32 s2, s2, 8
	s_add_i32 s16, s57, s2
	s_mov_b32 s15, s16
	s_add_i32 s14, s16, 0xfffffc00
	s_branch .LBB0_199

.LBB0_198:
	s_cmp_eq_u32 s32, 0
	s_cbranch_scc1 .Lpd_plain
	s_lshr_b32 s32, s32, 4
	s_and_b32 s2, s32, 15
	s_waitcnt lgkmcnt(0)
	s_cmp_eq_u32 s2, 15
	s_cbranch_scc1 .LBB0_138
	s_lshl_b32 s2, s2, 8
	s_add_i32 s16, s57, s2
	s_mov_b32 s15, s16
	s_add_i32 s14, s16, 0xfffffc00
	s_branch .LBB0_199
